# speedup vs baseline: 1.0105x; 1.0004x over previous
;     __device__ __forceinline__ bf16_t* U() const { return (bf16_t*)(ws + OFF_U); }
;     __device__ __forceinline__ bf16_t* Y() const { return (bf16_t*)(ws + OFF_Y); }
; DEV void st_bf4(bf16_t* p, float a, float b, float c, float d) { uint2 w; w.x = pk_bf16(a, b); w.y = pk_bf16(c, d); *(uint2*)p = w; }
; DEV void ld_bf4(const bf16_t* p, float (&v)[4]) { uint2 w = *(const uint2*)p; v[0] = bf_lo(w.x); v[1] = bf_hi(w.x); v[2] = bf_lo(w.y); v[3] = bf_hi(w.y); }
; DEV void sgu_job(const Params& p, int l, int c, int g, char* smem) {
;     ...
; #pragma unroll
;     for (int mi = 0; mi < 2; ++mi) {
;         const int i = wid * 32 + mi * 16 + fr, r = r0 + i;
;         const float bs = p.b_sgu[(l * 4 + g) * 128 + i];
; #pragma unroll
;         for (int ni = 0; ni < 6; ++ni) {
;             const int ch = g * 96 + ni * 16 + fq * 4;
;             float u[4]; ld_bf4(p.U() + (size_t)r * 384 + ch, u);
;             st_bf4(p.Y() + (size_t)r * 384 + ch, u[0] * (acc[mi][ni][0] + bs), u[1] * (acc[mi][ni][1] + bs), u[2] * (acc[mi][ni][2] + bs), u[3] * (acc[mi][ni][3] + bs));
;         }
;     }
.LBB0_1673:
	s_or_b64 exec, exec, s[4:5]
	v_add_u32_e32 v51, s6, v52
	v_lshl_add_u32 v52, s0, 7, v52
	v_readlane_b32 s0, v253, 43
	v_ashrrev_i32_e32 v53, 31, v52
	v_readlane_b32 s1, v253, 44
	v_mov_b64_e32 v[54:55], s[50:51]
	s_movk_i32 s4, 0x300
	v_lshl_add_u64 v[52:53], v[52:53], 2, s[0:1]
	v_mad_i64_i32 v[56:57], s[0:1], v51, s4, v[54:55]
	v_readlane_b32 s0, v252, 27
	flat_load_dword v58, v[52:53]
	v_readlane_b32 s1, v252, 28
	v_lshl_or_b32 v32, v59, 3, s0
	v_lshl_add_u64 v[62:63], v[56:57], 0, v[32:33]
	flat_load_dwordx2 v[96:97], v[62:63]
	flat_load_dwordx2 v[98:99], v[62:63] offset:32
	flat_load_dwordx2 v[100:101], v[62:63] offset:64
	flat_load_dwordx2 v[102:103], v[62:63] offset:96
	flat_load_dwordx2 v[104:105], v[62:63] offset:128
	flat_load_dwordx2 v[106:107], v[62:63] offset:160
	s_waitcnt vmcnt(0) lgkmcnt(0)
	v_pk_add_f32 v[46:47], v[46:47], v[58:59] op_sel_hi:[1,0]
	v_pk_add_f32 v[48:49], v[48:49], v[58:59] op_sel_hi:[1,0]
	v_pk_add_f32 v[42:43], v[42:43], v[58:59] op_sel_hi:[1,0]
	v_pk_add_f32 v[44:45], v[44:45], v[58:59] op_sel_hi:[1,0]
	v_lshlrev_b32_e32 v64, 16, v96
	v_and_b32_e32 v65, 0xffff0000, v96
	v_lshlrev_b32_e32 v66, 16, v97
	v_and_b32_e32 v67, 0xffff0000, v97
	v_mov_b64_e32 v[56:57], s[52:53]
	v_mad_i64_i32 v[60:61], s[0:1], v51, s4, v[56:57]
	v_pk_mul_f32 v[46:47], v[46:47], v[64:65]
	v_pk_mul_f32 v[48:49], v[48:49], v[66:67]
	v_lshl_add_u64 v[60:61], v[60:61], 0, v[32:33]
	v_cvt_pk_bf16_f32 v46, v46, v47
	v_cvt_pk_bf16_f32 v47, v48, v49
	flat_store_dwordx2 v[60:61], v[46:47]
	v_pk_add_f32 v[38:39], v[38:39], v[58:59] op_sel_hi:[1,0]
	v_pk_add_f32 v[40:41], v[40:41], v[58:59] op_sel_hi:[1,0]
	v_pk_add_f32 v[34:35], v[34:35], v[58:59] op_sel_hi:[1,0]
	v_pk_add_f32 v[36:37], v[36:37], v[58:59] op_sel_hi:[1,0]
	v_pk_add_f32 v[24:25], v[24:25], v[58:59] op_sel_hi:[1,0]
	v_pk_add_f32 v[26:27], v[26:27], v[58:59] op_sel_hi:[1,0]
	v_pk_add_f32 v[28:29], v[28:29], v[58:59] op_sel_hi:[1,0]
	v_lshlrev_b32_e32 v48, 16, v98
	v_and_b32_e32 v49, 0xffff0000, v98
	v_lshlrev_b32_e32 v46, 16, v99
	v_and_b32_e32 v47, 0xffff0000, v99
	v_pk_mul_f32 v[42:43], v[42:43], v[48:49]
	v_pk_mul_f32 v[44:45], v[44:45], v[46:47]
	v_cvt_pk_bf16_f32 v42, v42, v43
	v_cvt_pk_bf16_f32 v43, v44, v45
	flat_store_dwordx2 v[60:61], v[42:43] offset:32
	v_lshlrev_b32_e32 v44, 16, v100
	v_and_b32_e32 v45, 0xffff0000, v100
	v_lshlrev_b32_e32 v42, 16, v101
	v_and_b32_e32 v43, 0xffff0000, v101
	v_pk_mul_f32 v[38:39], v[38:39], v[44:45]
	v_pk_mul_f32 v[40:41], v[40:41], v[42:43]
	v_cvt_pk_bf16_f32 v38, v38, v39
	v_cvt_pk_bf16_f32 v39, v40, v41
	flat_store_dwordx2 v[60:61], v[38:39] offset:64
	v_lshlrev_b32_e32 v40, 16, v102
	v_and_b32_e32 v41, 0xffff0000, v102
	v_lshlrev_b32_e32 v38, 16, v103
	v_and_b32_e32 v39, 0xffff0000, v103
	v_pk_mul_f32 v[34:35], v[34:35], v[40:41]
	v_pk_mul_f32 v[36:37], v[36:37], v[38:39]
	v_cvt_pk_bf16_f32 v34, v34, v35
	v_cvt_pk_bf16_f32 v35, v36, v37
	flat_store_dwordx2 v[60:61], v[34:35] offset:96
	v_lshlrev_b32_e32 v36, 16, v104
	v_and_b32_e32 v37, 0xffff0000, v104
	v_lshlrev_b32_e32 v34, 16, v105
	v_and_b32_e32 v35, 0xffff0000, v105
	v_pk_mul_f32 v[24:25], v[24:25], v[36:37]
	v_pk_mul_f32 v[26:27], v[26:27], v[34:35]
	v_cvt_pk_bf16_f32 v24, v24, v25
	v_cvt_pk_bf16_f32 v25, v26, v27
	flat_store_dwordx2 v[60:61], v[24:25] offset:128
	v_lshlrev_b32_e32 v26, 16, v106
	v_and_b32_e32 v27, 0xffff0000, v106
	v_lshlrev_b32_e32 v24, 16, v107
	v_and_b32_e32 v25, 0xffff0000, v107
	v_pk_mul_f32 v[26:27], v[28:29], v[26:27]
	v_pk_add_f32 v[28:29], v[30:31], v[58:59] op_sel_hi:[1,0]
	v_cvt_pk_bf16_f32 v26, v26, v27
	v_pk_mul_f32 v[24:25], v[28:29], v[24:25]
	s_nop 0
	v_cvt_pk_bf16_f32 v27, v24, v25
	flat_store_dwordx2 v[60:61], v[26:27] offset:160
	v_add_u32_e32 v27, s6, v50
	v_mad_i64_i32 v[24:25], s[0:1], v27, s4, v[54:55]
	v_lshl_add_u64 v[28:29], v[24:25], 0, v[32:33]
	flat_load_dword v26, v[52:53] offset:64
	flat_load_dwordx2 v[108:109], v[28:29]
	flat_load_dwordx2 v[110:111], v[28:29] offset:32
	flat_load_dwordx2 v[112:113], v[28:29] offset:64
	flat_load_dwordx2 v[114:115], v[28:29] offset:96
	flat_load_dwordx2 v[116:117], v[28:29] offset:128
	flat_load_dwordx2 v[118:119], v[28:29] offset:160
	s_waitcnt vmcnt(0) lgkmcnt(0)
	v_pk_add_f32 v[20:21], v[20:21], v[26:27] op_sel_hi:[1,0]
	v_lshlrev_b32_e32 v30, 16, v108
	v_and_b32_e32 v31, 0xffff0000, v108
	v_lshlrev_b32_e32 v34, 16, v109
	v_and_b32_e32 v35, 0xffff0000, v109
	v_pk_add_f32 v[22:23], v[22:23], v[26:27] op_sel_hi:[1,0]
	v_mad_i64_i32 v[24:25], s[0:1], v27, s4, v[56:57]
	v_pk_mul_f32 v[20:21], v[20:21], v[30:31]
	v_pk_mul_f32 v[22:23], v[22:23], v[34:35]
	v_lshl_add_u64 v[24:25], v[24:25], 0, v[32:33]
	v_cvt_pk_bf16_f32 v20, v20, v21
	v_cvt_pk_bf16_f32 v21, v22, v23
	flat_store_dwordx2 v[24:25], v[20:21]
	v_pk_add_f32 v[16:17], v[16:17], v[26:27] op_sel_hi:[1,0]
	v_pk_add_f32 v[18:19], v[18:19], v[26:27] op_sel_hi:[1,0]
	v_pk_add_f32 v[12:13], v[12:13], v[26:27] op_sel_hi:[1,0]
	v_pk_add_f32 v[14:15], v[14:15], v[26:27] op_sel_hi:[1,0]
	v_pk_add_f32 v[8:9], v[8:9], v[26:27] op_sel_hi:[1,0]
	v_pk_add_f32 v[10:11], v[10:11], v[26:27] op_sel_hi:[1,0]
	v_pk_add_f32 v[4:5], v[4:5], v[26:27] op_sel_hi:[1,0]
	v_pk_add_f32 v[6:7], v[6:7], v[26:27] op_sel_hi:[1,0]
	v_pk_add_f32 v[0:1], v[0:1], v[26:27] op_sel_hi:[1,0]
	v_pk_add_f32 v[2:3], v[2:3], v[26:27] op_sel_hi:[1,0]
	v_lshlrev_b32_e32 v22, 16, v110
	v_and_b32_e32 v23, 0xffff0000, v110
	v_lshlrev_b32_e32 v20, 16, v111
	v_and_b32_e32 v21, 0xffff0000, v111
	v_pk_mul_f32 v[16:17], v[16:17], v[22:23]
	v_pk_mul_f32 v[18:19], v[18:19], v[20:21]
	v_cvt_pk_bf16_f32 v16, v16, v17
	v_cvt_pk_bf16_f32 v17, v18, v19
	flat_store_dwordx2 v[24:25], v[16:17] offset:32
	v_lshlrev_b32_e32 v18, 16, v112
	v_and_b32_e32 v19, 0xffff0000, v112
	v_lshlrev_b32_e32 v16, 16, v113
	v_and_b32_e32 v17, 0xffff0000, v113
	v_pk_mul_f32 v[12:13], v[12:13], v[18:19]
	v_pk_mul_f32 v[14:15], v[14:15], v[16:17]
	v_cvt_pk_bf16_f32 v12, v12, v13
	v_cvt_pk_bf16_f32 v13, v14, v15
	flat_store_dwordx2 v[24:25], v[12:13] offset:64
	v_lshlrev_b32_e32 v14, 16, v114
	v_and_b32_e32 v15, 0xffff0000, v114
	v_lshlrev_b32_e32 v12, 16, v115
	v_and_b32_e32 v13, 0xffff0000, v115
	v_pk_mul_f32 v[8:9], v[8:9], v[14:15]
	v_pk_mul_f32 v[10:11], v[10:11], v[12:13]
	v_cvt_pk_bf16_f32 v8, v8, v9
	v_cvt_pk_bf16_f32 v9, v10, v11
	flat_store_dwordx2 v[24:25], v[8:9] offset:96
	v_lshlrev_b32_e32 v10, 16, v116
	v_and_b32_e32 v11, 0xffff0000, v116
	v_lshlrev_b32_e32 v8, 16, v117
	v_and_b32_e32 v9, 0xffff0000, v117
	v_pk_mul_f32 v[4:5], v[4:5], v[10:11]
	v_pk_mul_f32 v[6:7], v[6:7], v[8:9]
	v_cvt_pk_bf16_f32 v4, v4, v5
	v_cvt_pk_bf16_f32 v5, v6, v7
	flat_store_dwordx2 v[24:25], v[4:5] offset:128
	v_lshlrev_b32_e32 v6, 16, v118
	v_and_b32_e32 v7, 0xffff0000, v118
	v_lshlrev_b32_e32 v4, 16, v119
	v_and_b32_e32 v5, 0xffff0000, v119
	v_pk_mul_f32 v[0:1], v[0:1], v[6:7]
	v_pk_mul_f32 v[2:3], v[2:3], v[4:5]
	v_cvt_pk_bf16_f32 v0, v0, v1
	v_cvt_pk_bf16_f32 v1, v2, v3
	flat_store_dwordx2 v[24:25], v[0:1] offset:160
	s_waitcnt lgkmcnt(0)
	s_barrier
